# grid barrier: non-leader workgroups poll the top-level generation word directly instead of the per-XCD generation word (one fewer hop per barrier), on top of v030
# baseline (speedup 1.0000x reference)
; DI unsigned xb_ld(unsigned* p)              { return __hip_atomic_load(p, __ATOMIC_RELAXED, __HIP_MEMORY_SCOPE_AGENT); }
; DI unsigned xb_add(unsigned* p, unsigned v) { return __hip_atomic_fetch_add(p, v, __ATOMIC_RELAXED, __HIP_MEMORY_SCOPE_AGENT); }
; #define XB_SPIN(cond, bar) do { unsigned _sp = 0; while (cond) { __builtin_amdgcn_s_sleep(1); \
;     if ((++_sp & 255u) == 0u) { if (xb_ld(&(bar)[XB_TMO])) break; if (_sp > XB_SPIN_CAP) { atomicAdd(&(bar)[XB_TMO], 1u); break; } } } } while (0)
; DI void xcd_barrier(const XcdBarrier& b) {
;     ...
;         const unsigned old = xb_add(&bar[XB_XSUB(b.x)], 1u);
;         const unsigned gen = old / nloc;
;         if (old + 1u == (gen + 1u) * nloc) {
;             __builtin_amdgcn_fence(__ATOMIC_RELEASE, "agent");
;             asm volatile("s_waitcnt vmcnt(0)" ::: "memory");
;             const unsigned og = xb_add(&bar[XB_TOP], 1u);
;             const unsigned tg = og / nx;
;             if (og + 1u == (tg + 1u) * nx) xb_add(&bar[XB_TOPGEN], 1u);
;             else XB_SPIN(xb_ld(&bar[XB_TOPGEN]) == tg, bar);
;             __builtin_amdgcn_fence(__ATOMIC_ACQUIRE, "agent");
;             xb_add(&bar[XB_XGEN(b.x)], 1u);
;             asm volatile("s_waitcnt vmcnt(0)" ::: "memory");
;         } else {
;             XB_SPIN(xb_ld(&bar[XB_XGEN(b.x)]) == gen, bar);
.LBB0_253:
	s_or_b64 exec, exec, s[4:5]
	v_cvt_f32_u32_e32 v7, v5
	s_waitcnt vmcnt(0)
	v_readfirstlane_b32 s4, v6
	v_sub_u32_e32 v6, 0, v5
	v_rcp_iflag_f32_e32 v7, v7
	v_add_u32_e32 v8, s4, v4
	v_mul_f32_e32 v7, 0x4f7ffffe, v7
	v_cvt_u32_f32_e32 v7, v7
	v_mul_lo_u32 v4, v6, v7
	v_mul_hi_u32 v4, v7, v4
	v_add_u32_e32 v4, v7, v4
	v_mul_hi_u32 v4, v8, v4
	v_mul_lo_u32 v6, v4, v5
	v_sub_u32_e32 v6, v8, v6
	v_add_u32_e32 v7, 1, v4
	v_sub_u32_e32 v9, v6, v5
	v_cmp_ge_u32_e32 vcc, v6, v5
	s_nop 1
	v_cndmask_b32_e32 v4, v4, v7, vcc
	v_cndmask_b32_e32 v6, v6, v9, vcc
	v_add_u32_e32 v7, 1, v4
	v_cmp_ge_u32_e32 vcc, v6, v5
	v_add_u32_e32 v6, 1, v8
	s_nop 0
	v_cndmask_b32_e32 v4, v4, v7, vcc
	v_mul_lo_u32 v7, v5, v4
	v_add_u32_e32 v5, v7, v5
	v_cmp_ne_u32_e32 vcc, v6, v5
	s_and_saveexec_b64 s[4:5], vcc
	s_xor_b64 s[4:5], exec, s[4:5]
	s_cbranch_execz .LBB0_267
	v_readlane_b32 s6, v253, 52
	v_readlane_b32 s7, v253, 53
	s_waitcnt lgkmcnt(0)
	s_nop 3
	global_load_dword v3, v2, s[6:7] sc1
	s_waitcnt vmcnt(0)
	v_cmp_eq_u32_e32 vcc, v3, v4
	s_and_saveexec_b64 s[6:7], vcc
	s_cbranch_execz .LBB0_266
	s_mov_b32 s19, 1
	s_mov_b64 s[8:9], 0
	s_branch .LBB0_257

; DI unsigned xb_ld(unsigned* p)              { return __hip_atomic_load(p, __ATOMIC_RELAXED, __HIP_MEMORY_SCOPE_AGENT); }
; #define XB_SPIN(cond, bar) do { unsigned _sp = 0; while (cond) { __builtin_amdgcn_s_sleep(1); \
;     if ((++_sp & 255u) == 0u) { if (xb_ld(&(bar)[XB_TMO])) break; if (_sp > XB_SPIN_CAP) { atomicAdd(&(bar)[XB_TMO], 1u); break; } } } } while (0)
; DI void xcd_barrier(const XcdBarrier& b) {
;     ...
;             XB_SPIN(xb_ld(&bar[XB_XGEN(b.x)]) == gen, bar);
.LBB0_259:
	v_readlane_b32 s12, v253, 52
	v_readlane_b32 s13, v253, 53
	s_add_i32 s19, s19, 1
	s_mov_b64 s[14:15], -1
	s_nop 2
	global_load_dword v3, v2, s[12:13] sc1
	s_waitcnt vmcnt(0)
	v_cmp_ne_u32_e32 vcc, v3, v4
	s_orn2_b64 s[12:13], vcc, exec
	s_branch .LBB0_256

; DI unsigned xb_ld(unsigned* p)              { return __hip_atomic_load(p, __ATOMIC_RELAXED, __HIP_MEMORY_SCOPE_AGENT); }
; DI unsigned xb_add(unsigned* p, unsigned v) { return __hip_atomic_fetch_add(p, v, __ATOMIC_RELAXED, __HIP_MEMORY_SCOPE_AGENT); }
; #define XB_SPIN(cond, bar) do { unsigned _sp = 0; while (cond) { __builtin_amdgcn_s_sleep(1); \
;     if ((++_sp & 255u) == 0u) { if (xb_ld(&(bar)[XB_TMO])) break; if (_sp > XB_SPIN_CAP) { atomicAdd(&(bar)[XB_TMO], 1u); break; } } } } while (0)
; DI void xcd_barrier(const XcdBarrier& b) {
;     ...
;         const unsigned old = xb_add(&bar[XB_XSUB(b.x)], 1u);
;         const unsigned gen = old / nloc;
;         if (old + 1u == (gen + 1u) * nloc) {
;             __builtin_amdgcn_fence(__ATOMIC_RELEASE, "agent");
;             asm volatile("s_waitcnt vmcnt(0)" ::: "memory");
;             const unsigned og = xb_add(&bar[XB_TOP], 1u);
;             const unsigned tg = og / nx;
;             if (og + 1u == (tg + 1u) * nx) xb_add(&bar[XB_TOPGEN], 1u);
;             else XB_SPIN(xb_ld(&bar[XB_TOPGEN]) == tg, bar);
;             __builtin_amdgcn_fence(__ATOMIC_ACQUIRE, "agent");
;             xb_add(&bar[XB_XGEN(b.x)], 1u);
;             asm volatile("s_waitcnt vmcnt(0)" ::: "memory");
;         } else {
;             XB_SPIN(xb_ld(&bar[XB_XGEN(b.x)]) == gen, bar);
.LBB0_351:
	s_or_b64 exec, exec, s[4:5]
	v_cvt_f32_u32_e32 v7, v5
	s_waitcnt vmcnt(0)
	v_readfirstlane_b32 s4, v6
	v_sub_u32_e32 v6, 0, v5
	v_rcp_iflag_f32_e32 v7, v7
	v_add_u32_e32 v8, s4, v3
	v_mul_f32_e32 v7, 0x4f7ffffe, v7
	v_cvt_u32_f32_e32 v7, v7
	v_mul_lo_u32 v3, v6, v7
	v_mul_hi_u32 v3, v7, v3
	v_add_u32_e32 v3, v7, v3
	v_mul_hi_u32 v3, v8, v3
	v_mul_lo_u32 v6, v3, v5
	v_sub_u32_e32 v6, v8, v6
	v_add_u32_e32 v7, 1, v3
	v_cmp_ge_u32_e32 vcc, v6, v5
	s_nop 1
	v_cndmask_b32_e32 v3, v3, v7, vcc
	v_sub_u32_e32 v7, v6, v5
	v_cndmask_b32_e32 v6, v6, v7, vcc
	v_add_u32_e32 v7, 1, v3
	v_cmp_ge_u32_e32 vcc, v6, v5
	v_add_u32_e32 v6, 1, v8
	s_nop 0
	v_cndmask_b32_e32 v3, v3, v7, vcc
	v_mul_lo_u32 v7, v5, v3
	v_add_u32_e32 v5, v7, v5
	v_cmp_ne_u32_e32 vcc, v6, v5
	s_and_saveexec_b64 s[4:5], vcc
	s_xor_b64 s[4:5], exec, s[4:5]
	s_cbranch_execz .LBB0_365
	v_readlane_b32 s6, v253, 52
	v_readlane_b32 s7, v253, 53
	s_waitcnt lgkmcnt(0)
	s_nop 3
	global_load_dword v4, v2, s[6:7] sc1
	s_waitcnt vmcnt(0)
	v_cmp_eq_u32_e32 vcc, v4, v3
	s_and_saveexec_b64 s[6:7], vcc
	s_cbranch_execz .LBB0_364
	s_mov_b32 s19, 1
	s_mov_b64 s[8:9], 0
	s_branch .LBB0_355

; DI unsigned xb_ld(unsigned* p)              { return __hip_atomic_load(p, __ATOMIC_RELAXED, __HIP_MEMORY_SCOPE_AGENT); }
; DI unsigned xb_add(unsigned* p, unsigned v) { return __hip_atomic_fetch_add(p, v, __ATOMIC_RELAXED, __HIP_MEMORY_SCOPE_AGENT); }
; #define XB_SPIN(cond, bar) do { unsigned _sp = 0; while (cond) { __builtin_amdgcn_s_sleep(1); \
;     if ((++_sp & 255u) == 0u) { if (xb_ld(&(bar)[XB_TMO])) break; if (_sp > XB_SPIN_CAP) { atomicAdd(&(bar)[XB_TMO], 1u); break; } } } } while (0)
; DI void xcd_barrier(const XcdBarrier& b) {
;     ...
;         const unsigned old = xb_add(&bar[XB_XSUB(b.x)], 1u);
;         const unsigned gen = old / nloc;
;         if (old + 1u == (gen + 1u) * nloc) {
;             __builtin_amdgcn_fence(__ATOMIC_RELEASE, "agent");
;             asm volatile("s_waitcnt vmcnt(0)" ::: "memory");
;             const unsigned og = xb_add(&bar[XB_TOP], 1u);
;             const unsigned tg = og / nx;
;             if (og + 1u == (tg + 1u) * nx) xb_add(&bar[XB_TOPGEN], 1u);
;             else XB_SPIN(xb_ld(&bar[XB_TOPGEN]) == tg, bar);
;             __builtin_amdgcn_fence(__ATOMIC_ACQUIRE, "agent");
;             xb_add(&bar[XB_XGEN(b.x)], 1u);
;             asm volatile("s_waitcnt vmcnt(0)" ::: "memory");
;         } else {
;             XB_SPIN(xb_ld(&bar[XB_XGEN(b.x)]) == gen, bar);
.LBB0_1704:
	s_or_b64 exec, exec, s[2:3]
	v_cvt_f32_u32_e32 v7, v5
	s_waitcnt vmcnt(0)
	v_readfirstlane_b32 s2, v6
	v_sub_u32_e32 v6, 0, v5
	v_rcp_iflag_f32_e32 v7, v7
	v_add_u32_e32 v8, s2, v3
	v_mul_f32_e32 v7, 0x4f7ffffe, v7
	v_cvt_u32_f32_e32 v7, v7
	v_mul_lo_u32 v3, v6, v7
	v_mul_hi_u32 v3, v7, v3
	v_add_u32_e32 v3, v7, v3
	v_mul_hi_u32 v3, v8, v3
	v_mul_lo_u32 v6, v3, v5
	v_sub_u32_e32 v6, v8, v6
	v_add_u32_e32 v7, 1, v3
	v_cmp_ge_u32_e32 vcc, v6, v5
	s_nop 1
	v_cndmask_b32_e32 v3, v3, v7, vcc
	v_sub_u32_e32 v7, v6, v5
	v_cndmask_b32_e32 v6, v6, v7, vcc
	v_add_u32_e32 v7, 1, v3
	v_cmp_ge_u32_e32 vcc, v6, v5
	v_add_u32_e32 v6, 1, v8
	s_nop 0
	v_cndmask_b32_e32 v3, v3, v7, vcc
	v_mul_lo_u32 v7, v5, v3
	v_add_u32_e32 v5, v7, v5
	v_cmp_ne_u32_e32 vcc, v6, v5
	s_and_saveexec_b64 s[2:3], vcc
	s_xor_b64 s[2:3], exec, s[2:3]
	s_cbranch_execz .LBB0_1718
	v_readlane_b32 s4, v253, 52
	v_readlane_b32 s5, v253, 53
	s_waitcnt lgkmcnt(0)
	s_nop 3
	global_load_dword v4, v2, s[4:5] sc1
	s_waitcnt vmcnt(0)
	v_cmp_eq_u32_e32 vcc, v4, v3
	s_and_saveexec_b64 s[4:5], vcc
	s_cbranch_execz .LBB0_1717
	s_mov_b32 s16, 1
	s_mov_b64 s[6:7], 0
	s_branch .LBB0_1708
